# attention loop: per-tile 64-bit multiply-add address computation replaced by running K/V DMA addresses advanced with one 64-bit add each
# speedup vs baseline: 1.0063x; 1.0013x over previous
; #define ATT_WAITBAR(N) do { asm volatile("s_waitcnt vmcnt(" #N ") lgkmcnt(0)" ::: "memory"); __builtin_amdgcn_s_barrier(); asm volatile("" ::: "memory"); } while (0)
; __device__ __forceinline__ void attn_item(CP& P, int L, int sq, int hh, int qt, float lam, float lam_init, LAS unsigned char* lds) {
;     ...
;     bool far_ = false;
;     ATT_DMA(0, 0); ATT_DMA((1 < ntiles ? 1 : ntiles - 1), 1);
;     ATT_WAITBAR(4);
;     bf16x8 kf[8];
;     for (int t = 0; t < ntiles; ++t) {
;         { const int tn = (t + 2 < ntiles) ? t + 2 : ntiles - 1; ATT_DMA(tn, (t + 2) & 3); }
;         const int k0_ = t * 64; const bool farR_ = (k0_ - (q0w + 31) >= 128), farL_ = (q0w - (k0_ + 63) >= 128); far_ = farR_ || farL_;
;         const float cinit_ = (far_ ? (farR_ ? tbl[256] : tbl[0]) : 0.f) - mref;
.LBB0_65:
	s_nop 8
	v_max_f32_e32 v4, v17, v17
	v_max_f32_e32 v5, v33, v33
	v_max_f32_e32 v4, v5, v4
	v_max_f32_e32 v5, v18, v18
	v_max_f32_e32 v6, v34, v34
	v_max_f32_e32 v5, v6, v5
	v_max_f32_e32 v6, v19, v19
	v_max_f32_e32 v7, v35, v35
	v_max3_f32 v4, v32, v16, v4
	v_max_f32_e32 v6, v7, v6
	v_max3_f32 v4, v4, v5, v6
	v_max_f32_e32 v5, v20, v20
	v_max_f32_e32 v6, v36, v36
	v_max_f32_e32 v5, v6, v5
	v_max_f32_e32 v6, v21, v21
	v_max_f32_e32 v7, v37, v37
	v_max_f32_e32 v6, v7, v6
	v_max3_f32 v4, v4, v5, v6
	v_max_f32_e32 v5, v22, v22
	v_max_f32_e32 v6, v38, v38
	v_max_f32_e32 v5, v6, v5
	v_max_f32_e32 v6, v23, v23
	v_max_f32_e32 v7, v39, v39
	v_max_f32_e32 v6, v7, v6
	v_max3_f32 v4, v4, v5, v6
	v_max_f32_e32 v5, v24, v24
	v_max_f32_e32 v6, v40, v40
	v_max_f32_e32 v5, v6, v5
	v_max_f32_e32 v6, v25, v25
	v_max_f32_e32 v7, v41, v41
	v_max_f32_e32 v6, v7, v6
	v_max3_f32 v4, v4, v5, v6
	v_max_f32_e32 v5, v26, v26
	v_max_f32_e32 v6, v42, v42
	v_max_f32_e32 v5, v6, v5
	v_max_f32_e32 v6, v27, v27
	v_max_f32_e32 v7, v43, v43
	v_max_f32_e32 v6, v7, v6
	v_max3_f32 v4, v4, v5, v6
	v_max_f32_e32 v5, v28, v28
	v_max_f32_e32 v6, v44, v44
	v_max_f32_e32 v5, v6, v5
	v_max_f32_e32 v6, v29, v29
	v_max_f32_e32 v7, v45, v45
	v_max_f32_e32 v6, v7, v6
	v_max3_f32 v4, v4, v5, v6
	v_max_f32_e32 v5, v30, v30
	v_max_f32_e32 v6, v46, v46
	v_max_f32_e32 v5, v6, v5
	v_max_f32_e32 v6, v31, v31
	v_max_f32_e32 v7, v47, v47
	v_max_f32_e32 v6, v7, v6
	v_max3_f32 v4, v4, v5, v6
	v_and_b32_e32 v6, 64, v227
	v_xor_b32_e32 v5, 32, v227
	v_add_u32_e32 v6, 64, v6
	v_cmp_lt_i32_e32 vcc, v5, v6
	v_bfe_u32 v1, v48, 2, 2
	v_lshlrev_b32_e32 v0, 3, v48
	v_cndmask_b32_e32 v5, v227, v5, vcc
	v_lshlrev_b32_e32 v129, 2, v5
	ds_bpermute_b32 v5, v129, v4
	v_or_b32_e32 v2, v127, v1
	v_lshlrev_b32_e32 v3, 1, v48
	v_lshlrev_b32_e32 v2, 8, v2
	v_and_b32_e32 v3, 32, v3
	v_and_b32_e32 v0, 24, v0
	v_or3_b32 v138, v0, v3, v2
	s_waitcnt lgkmcnt(0)
	v_max_f32_e32 v0, v5, v5
	v_max_f32_e32 v48, v4, v0
	v_sub_f32_e32 v32, v32, v48
	v_sub_f32_e32 v16, v16, v48
	v_exp_f32_e32 v50, v32
	v_exp_f32_e32 v51, v16
	v_sub_f32_e32 v16, v33, v48
	v_sub_f32_e32 v17, v17, v48
	v_exp_f32_e32 v16, v16
	v_exp_f32_e32 v17, v17
	v_sub_f32_e32 v32, v34, v48
	v_sub_f32_e32 v18, v18, v48
	v_exp_f32_e32 v32, v32
	v_exp_f32_e32 v33, v18
	v_sub_f32_e32 v18, v35, v48
	v_sub_f32_e32 v19, v19, v48
	v_exp_f32_e32 v18, v18
	v_exp_f32_e32 v19, v19
	v_sub_f32_e32 v36, v36, v48
	v_sub_f32_e32 v20, v20, v48
	v_pk_add_f32 v[34:35], v[50:51], 0 op_sel_hi:[1,0]
	v_exp_f32_e32 v52, v36
	v_exp_f32_e32 v53, v20
	v_sub_f32_e32 v20, v37, v48
	v_sub_f32_e32 v21, v21, v48
	v_pk_add_f32 v[34:35], v[16:17], v[34:35]
	v_exp_f32_e32 v20, v20
	v_exp_f32_e32 v21, v21
	v_sub_f32_e32 v36, v38, v48
	v_sub_f32_e32 v22, v22, v48
	v_pk_add_f32 v[34:35], v[32:33], v[34:35]
	v_exp_f32_e32 v36, v36
	v_exp_f32_e32 v37, v22
	v_sub_f32_e32 v22, v39, v48
	v_sub_f32_e32 v23, v23, v48
	v_pk_add_f32 v[34:35], v[18:19], v[34:35]
	v_exp_f32_e32 v22, v22
	v_exp_f32_e32 v23, v23
	v_sub_f32_e32 v38, v40, v48
	v_sub_f32_e32 v24, v24, v48
	v_pk_add_f32 v[34:35], v[52:53], v[34:35]
	v_exp_f32_e32 v38, v38
	v_exp_f32_e32 v39, v24
	v_sub_f32_e32 v24, v41, v48
	v_sub_f32_e32 v25, v25, v48
	v_pk_add_f32 v[34:35], v[20:21], v[34:35]
	v_exp_f32_e32 v24, v24
	v_exp_f32_e32 v25, v25
	v_sub_f32_e32 v40, v42, v48
	v_sub_f32_e32 v26, v26, v48
	v_pk_add_f32 v[34:35], v[36:37], v[34:35]
	v_exp_f32_e32 v40, v40
	v_exp_f32_e32 v41, v26
	v_sub_f32_e32 v26, v43, v48
	v_sub_f32_e32 v27, v27, v48
	v_pk_add_f32 v[34:35], v[22:23], v[34:35]
	v_exp_f32_e32 v26, v26
	v_exp_f32_e32 v27, v27
	v_sub_f32_e32 v42, v44, v48
	v_sub_f32_e32 v28, v28, v48
	v_pk_add_f32 v[34:35], v[38:39], v[34:35]
	v_exp_f32_e32 v42, v42
	v_exp_f32_e32 v43, v28
	v_sub_f32_e32 v28, v45, v48
	v_sub_f32_e32 v29, v29, v48
	v_pk_add_f32 v[34:35], v[24:25], v[34:35]
	v_exp_f32_e32 v28, v28
	v_exp_f32_e32 v29, v29
	v_sub_f32_e32 v44, v46, v48
	v_sub_f32_e32 v30, v30, v48
	v_pk_add_f32 v[34:35], v[40:41], v[34:35]
	v_exp_f32_e32 v44, v44
	v_exp_f32_e32 v45, v30
	v_sub_f32_e32 v30, v47, v48
	v_sub_f32_e32 v31, v31, v48
	v_pk_add_f32 v[34:35], v[26:27], v[34:35]
	v_exp_f32_e32 v30, v30
	v_exp_f32_e32 v31, v31
	v_exp_f32_e64 v0, -v48
	v_pk_add_f32 v[34:35], v[42:43], v[34:35]
	s_lshl_b32 s2, s14, 7
	v_pk_add_f32 v[34:35], v[28:29], v[34:35]
	v_mul_f32_e32 v0, 0, v0
	v_pk_add_f32 v[34:35], v[44:45], v[34:35]
	v_cvt_pk_bf16_f32 v220, v50, v16
	v_pk_add_f32 v[34:35], v[30:31], v[34:35]
	v_sub_u32_e32 v16, v127, v128
	v_pk_add_f32 v[34:35], v[34:35], v[34:35] op_sel_hi:[0,1]
	s_and_b64 s[0:1], s[0:1], exec
	v_mov_b32_e32 v14, v0
	v_mov_b32_e32 v15, v0
	s_waitcnt vmcnt(4) lgkmcnt(0)
	s_barrier
	v_mov_b32_e32 v49, v0
	v_mov_b32_e32 v34, v193
	v_subrev_u32_e32 v16, s10, v16
	s_cselect_b32 s15, 32, 64
	v_lshlrev_b32_e32 v139, 6, v1
	v_mov_b32_e32 v1, v0
	v_mov_b32_e32 v2, v0
	v_mov_b32_e32 v3, v0
	v_mov_b32_e32 v4, v0
	v_mov_b32_e32 v5, v0
	v_mov_b32_e32 v6, v0
	v_mov_b32_e32 v7, v0
	v_mov_b32_e32 v8, v0
	v_mov_b32_e32 v9, v0
	v_mov_b32_e32 v10, v0
	v_mov_b32_e32 v11, v0
	v_mov_b32_e32 v12, v0
	v_mov_b32_e32 v13, v0
	v_pk_add_f32 v[124:125], v[48:49], v[34:35]
	v_cvt_pk_bf16_f32 v208, v39, v25
	v_cvt_pk_bf16_f32 v209, v41, v27
	v_cvt_pk_bf16_f32 v210, v43, v29
	v_cvt_pk_bf16_f32 v211, v45, v31
	v_cvt_pk_bf16_f32 v212, v51, v17
	v_cvt_pk_bf16_f32 v213, v33, v19
	v_cvt_pk_bf16_f32 v214, v53, v21
	v_cvt_pk_bf16_f32 v215, v37, v23
	v_cvt_pk_bf16_f32 v216, v38, v24
	v_cvt_pk_bf16_f32 v217, v40, v26
	v_cvt_pk_bf16_f32 v218, v42, v28
	v_cvt_pk_bf16_f32 v219, v44, v30
	v_cvt_pk_bf16_f32 v221, v32, v18
	v_cvt_pk_bf16_f32 v222, v52, v20
	v_cvt_pk_bf16_f32 v223, v36, v22
	v_subrev_u32_e32 v141, s20, v16
	v_mov_b64_e32 v[62:63], v[14:15]
	v_mov_b64_e32 v[46:47], v[14:15]
	v_mov_b64_e32 v[30:31], v[14:15]
	v_ashrrev_i32_e32 v115, 31, v114
	s_mov_b32 s14, 64
	s_mov_b32 s16, 1
	s_add_i32 s17, s15, -1
	v_add_u32_e32 v140, 0, v138
	v_xor_b32_e32 v137, 64, v139
	v_xor_b32_e32 v136, 0x80, v139
	v_xor_b32_e32 v135, 0xc0, v139
	s_add_i32 s18, s19, 0x9e
	s_addk_i32 s19, 0xff42
	s_mov_b32 s20, 0x20000
	v_mov_b64_e32 v[60:61], v[12:13]
	v_mov_b64_e32 v[58:59], v[10:11]
	v_mov_b64_e32 v[56:57], v[8:9]
	v_mov_b64_e32 v[54:55], v[6:7]
	v_mov_b64_e32 v[52:53], v[4:5]
	v_mov_b64_e32 v[50:51], v[2:3]
	v_mov_b64_e32 v[48:49], v[0:1]
	v_mov_b64_e32 v[44:45], v[12:13]
	v_mov_b64_e32 v[42:43], v[10:11]
	v_mov_b64_e32 v[40:41], v[8:9]
	v_mov_b64_e32 v[38:39], v[6:7]
	v_mov_b64_e32 v[36:37], v[4:5]
	v_mov_b64_e32 v[34:35], v[2:3]
	v_mov_b64_e32 v[32:33], v[0:1]
	v_mov_b64_e32 v[28:29], v[12:13]
	v_mov_b64_e32 v[26:27], v[10:11]
	v_mov_b64_e32 v[24:25], v[8:9]
	v_mov_b64_e32 v[22:23], v[6:7]
	v_mov_b64_e32 v[20:21], v[4:5]
	v_mov_b64_e32 v[18:19], v[2:3]
	v_mov_b64_e32 v[16:17], v[0:1]
	s_mov_b32 s22, 0x210000
	s_mov_b32 s23, 0
	v_lshl_add_u64 v[116:117], s[22:23], 0, v[116:117]
	v_lshl_add_u64 v[118:119], s[22:23], 0, v[118:119]
	v_lshl_add_u64 v[120:121], s[22:23], 0, v[120:121]
	v_lshl_add_u64 v[122:123], s[22:23], 0, v[122:123]
	s_branch .LBB0_67
; __device__ __forceinline__ void attn_item(CP& P, int L, int sq, int hh, int qt, float lam, float lam_init, LAS unsigned char* lds) {
;     ...
;         { const int tn = (t + 2 < ntiles) ? t + 2 : ntiles - 1; ATT_DMA(tn, (t + 2) & 3); }
;         const int k0_ = t * 64; const bool farR_ = (k0_ - (q0w + 31) >= 128), farL_ = (q0w - (k0_ + 63) >= 128); far_ = farR_ || farL_;
;         const float cinit_ = (far_ ? (farR_ ? tbl[256] : tbl[0]) : 0.f) - mref;
.LBB0_67:
	s_add_i32 s0, s16, 2
	s_cmp_lt_i32 s0, s17
	s_cselect_b32 s22, 0xb0000, 0
	s_mov_b32 s23, 0
	s_add_i32 s0, s20, 0xffff8000
	s_and_b32 s0, s0, 0x18000
	s_add_i32 s5, s11, s0
	s_add_i32 s21, s5, 0x4000
	s_mov_b32 m0, s5
	s_nop 0
	global_load_lds_dwordx4 v[116:117], off
	v_lshl_add_u64 v[116:117], s[22:23], 0, v[116:117]
	s_mov_b32 m0, s21
	s_nop 0
	global_load_lds_dwordx4 v[118:119], off
	v_lshl_add_u64 v[118:119], s[22:23], 0, v[118:119]
	s_add_i32 m0, s5, 0x400
	s_nop 0
	global_load_lds_dwordx4 v[120:121], off
	v_lshl_add_u64 v[120:121], s[22:23], 0, v[120:121]
	s_add_i32 m0, s5, 0x4400
	s_cmp_le_u32 s14, s18
	global_load_lds_dwordx4 v[122:123], off
	v_lshl_add_u64 v[122:123], s[22:23], 0, v[122:123]
	s_cselect_b64 s[4:5], -1, 0
	s_cmp_ge_i32 s14, s19
	s_cselect_b64 s[0:1], -1, 0
	s_and_b64 s[0:1], s[4:5], s[0:1]
	s_and_b64 vcc, exec, s[0:1]
	v_mov_b32_e32 v64, 0
	s_cbranch_vccnz .LBB0_72
	s_and_b64 vcc, exec, s[4:5]
	s_cbranch_vccz .LBB0_70
	s_add_i32 s4, 0, 0x20000
	v_mov_b32_e32 v64, s4
	ds_read_b32 v64, v64
	s_cbranch_execz .LBB0_71
	s_branch .LBB0_72
